# attention static s_setprio 1 moved from waves 4-7 to waves 0-3 (other half), on top of v25
# speedup vs baseline: 1.0119x; 1.0060x over previous
; #define GAS __attribute__((address_space(1)))
; DI void phase_attn(const Ctx& C) {
;     const int lane = C.lane, w = C.wave, r = lane & 31, hh = lane >> 5;
;     const GAS bf16* QD = WSP(bf16, WS_QD); const GAS bf16* QW = WSP(bf16, WS_QW); const GAS uchar* DK = WSP(uchar, WS_DK); const GAS uchar* DVT = WSP(uchar, WS_DVT);
;     const GAS uchar* WK = WSP(uchar, WS_WK); const GAS uchar* WVT = WSP(uchar, WS_WVT); GAS bf16* ATT = WSP(bf16, WS_H);
;     float lam;
;     { const GAS float* lv = INP(I_ODLAM); const float a = wave_sum(lv[lane] * lv[64 + lane]), b = wave_sum(lv[128 + lane] * lv[192 + lane]); lam = __expf(a) - __expf(b) + LAM_INIT; }
;     if (w >= 4) __builtin_amdgcn_s_setprio(1);
.LBB0_2012:
	s_cmp_lt_i32 s78, 19
	s_cselect_b64 s[0:1], -1, 0
	s_cmp_gt_i32 s79, 18
	s_cselect_b64 s[2:3], -1, 0
	s_and_b64 s[0:1], s[0:1], s[2:3]
	s_andn2_b64 vcc, exec, s[0:1]
	s_cbranch_vccnz .LBB0_2116
	s_mov_b32 s3, 0
	s_mov_b32 s26, s62
	s_mov_b64 s[20:21], s[34:35]
	v_mov_b32_e32 v194, v1
	s_mov_b32 s27, s63
	s_mov_b64 s[0:1], s[74:75]
	v_readlane_b32 s4, v237, 0
	v_and_b32_e32 v193, 63, v194
	s_waitcnt vmcnt(3)
	v_lshlrev_b32_e32 v2, 2, v193
	v_readlane_b32 s6, v237, 2
	v_readlane_b32 s7, v237, 3
	s_nop 4
	global_load_dword v3, v2, s[6:7]
	global_load_dword v4, v2, s[6:7] offset:256
	global_load_dword v5, v2, s[6:7] offset:512
	global_load_dword v6, v2, s[6:7] offset:768
	v_mbcnt_lo_u32_b32 v2, -1, 0
	v_mbcnt_hi_u32_b32 v2, -1, v2
	s_waitcnt vmcnt(6)
	v_and_b32_e32 v7, 64, v2
	v_xor_b32_e32 v8, 1, v2
	v_add_u32_e32 v7, 64, v7
	v_cmp_lt_i32_e32 vcc, v8, v7
	v_xor_b32_e32 v9, 2, v2
	s_waitcnt vmcnt(5)
	v_xor_b32_e32 v10, 4, v2
	v_cndmask_b32_e32 v8, v2, v8, vcc
	v_lshlrev_b32_e32 v8, 2, v8
	v_cmp_lt_i32_e32 vcc, v9, v7
	v_xor_b32_e32 v11, 8, v2
	v_xor_b32_e32 v12, 16, v2
	v_cndmask_b32_e32 v9, v2, v9, vcc
	v_lshlrev_b32_e32 v9, 2, v9
	v_cmp_lt_i32_e32 vcc, v10, v7
	v_xor_b32_e32 v13, 32, v2
	v_readfirstlane_b32 s2, v194
	s_ashr_i32 s31, s2, 6
	s_cmp_lt_i32 s31, 4
	v_readlane_b32 s5, v237, 1
	v_readlane_b32 s8, v237, 4
	v_readlane_b32 s9, v237, 5
	v_readlane_b32 s10, v237, 6
	v_readlane_b32 s11, v237, 7
	s_waitcnt vmcnt(2)
	v_mul_f32_e32 v14, v3, v4
	ds_bpermute_b32 v14, v8, v14
	s_waitcnt vmcnt(0)
	v_mul_f32_e32 v15, v5, v6
	ds_bpermute_b32 v8, v8, v15
	s_waitcnt lgkmcnt(1)
	v_fmac_f32_e32 v14, v3, v4
	ds_bpermute_b32 v3, v9, v14
	s_waitcnt lgkmcnt(1)
	v_fmac_f32_e32 v8, v5, v6
	ds_bpermute_b32 v4, v9, v8
	v_cndmask_b32_e32 v5, v2, v10, vcc
	v_lshlrev_b32_e32 v5, 2, v5
	s_waitcnt lgkmcnt(1)
	v_add_f32_e32 v3, v14, v3
	ds_bpermute_b32 v6, v5, v3
	s_waitcnt lgkmcnt(1)
	v_add_f32_e32 v4, v8, v4
	ds_bpermute_b32 v5, v5, v4
	v_cmp_lt_i32_e32 vcc, v11, v7
	s_waitcnt lgkmcnt(1)
	v_add_f32_e32 v3, v3, v6
	v_cndmask_b32_e32 v8, v2, v11, vcc
	v_lshlrev_b32_e32 v8, 2, v8
	s_waitcnt lgkmcnt(0)
	v_add_f32_e32 v4, v4, v5
	ds_bpermute_b32 v5, v8, v3
	ds_bpermute_b32 v6, v8, v4
	v_cmp_lt_i32_e32 vcc, v12, v7
	s_waitcnt lgkmcnt(1)
	v_add_f32_e32 v3, v3, v5
	v_cndmask_b32_e32 v8, v2, v12, vcc
	v_lshlrev_b32_e32 v8, 2, v8
	s_waitcnt lgkmcnt(0)
	v_add_f32_e32 v4, v4, v6
	ds_bpermute_b32 v5, v8, v3
	ds_bpermute_b32 v6, v8, v4
	v_cmp_lt_i32_e32 vcc, v13, v7
	s_nop 1
	v_cndmask_b32_e32 v2, v2, v13, vcc
	v_lshlrev_b32_e32 v165, 2, v2
	s_waitcnt lgkmcnt(1)
	v_add_f32_e32 v2, v3, v5
	s_waitcnt lgkmcnt(0)
	v_add_f32_e32 v3, v4, v6
	ds_bpermute_b32 v4, v165, v2
	ds_bpermute_b32 v5, v165, v3
	s_cbranch_scc0 .LBB0_2015
	s_setprio 1
